# out-proj epilogue: loads/stores issued row-major so the two 64 B halves of a cache line go out back to back
# speedup vs baseline: 1.0063x; 1.0063x over previous
.LBB0_871:
	s_ashr_i32 s7, s54, 3
	s_mul_hi_i32 s9, s7, 0x6000
	s_mulk_i32 s7, 0x6000
	s_add_u32 s14, s58, s7
	s_addc_u32 s15, s59, s9
	v_readlane_b32 s98, v254, 0
	v_readlane_b32 s99, v254, 1
	s_mov_b64 s[100:101], s[48:49]
	v_and_b32_e32 v152, 15, v210
	v_bfe_u32 v153, v210, 4, 2
	v_lshlrev_b32_e32 v153, 2, v153
	v_sub_u32_e32 v153, v153, v152
	v_add_u32_e32 v154, v160, v153
	v_sub_u32_e32 v155, v162, v153
	v_lshl_add_u32 v154, s54, 8, v154
	v_lshl_add_u32 v155, s55, 8, v155
	v_lshlrev_b32_e32 v155, 2, v155
	v_lshl_add_u32 v164, v154, 13, v155
	v_add_u32_e32 v165, 0x2000, v164
	v_add_u32_e32 v166, 0x4000, v164
	v_add_u32_e32 v167, 0x6000, v164
	global_load_dword v98, v155, s[14:15]
	global_load_dword v100, v155, s[14:15] offset:64
	global_load_dword v102, v155, s[14:15] offset:512
	global_load_dword v104, v155, s[14:15] offset:576
	global_load_dword v190, v164, s[98:99]
	global_load_dword v194, v164, s[98:99] offset:64
	global_load_dword v198, v164, s[98:99] offset:512
	global_load_dword v202, v164, s[98:99] offset:576
	global_load_dword v191, v165, s[98:99]
	global_load_dword v195, v165, s[98:99] offset:64
	global_load_dword v199, v165, s[98:99] offset:512
	global_load_dword v203, v165, s[98:99] offset:576
	global_load_dword v192, v166, s[98:99]
	global_load_dword v196, v166, s[98:99] offset:64
	global_load_dword v200, v166, s[98:99] offset:512
	global_load_dword v204, v166, s[98:99] offset:576
	global_load_dword v193, v167, s[98:99]
	global_load_dword v197, v167, s[98:99] offset:64
	global_load_dword v201, v167, s[98:99] offset:512
	global_load_dword v205, v167, s[98:99] offset:576
	s_add_u32 s98, s98, 0x20000
	s_addc_u32 s99, s99, 0
	global_load_dword v152, v164, s[98:99]
	global_load_dword v156, v164, s[98:99] offset:64
	global_load_dword v106, v164, s[98:99] offset:512
	global_load_dword v110, v164, s[98:99] offset:576
	global_load_dword v153, v165, s[98:99]
	global_load_dword v157, v165, s[98:99] offset:64
	global_load_dword v107, v165, s[98:99] offset:512
	global_load_dword v111, v165, s[98:99] offset:576
	global_load_dword v154, v166, s[98:99]
	global_load_dword v158, v166, s[98:99] offset:64
	global_load_dword v108, v166, s[98:99] offset:512
	global_load_dword v112, v166, s[98:99] offset:576
	global_load_dword v155, v167, s[98:99]
	global_load_dword v159, v167, s[98:99] offset:64
	global_load_dword v109, v167, s[98:99] offset:512
	global_load_dword v113, v167, s[98:99] offset:576
	s_add_u32 s98, s98, 0x20000
	s_addc_u32 s99, s99, 0
	s_waitcnt vmcnt(16)
	v_pk_fma_f32 v[142:143], v[142:143], v[98:99], v[190:191] op_sel_hi:[1,0,1]
	v_pk_fma_f32 v[144:145], v[144:145], v[98:99], v[192:193] op_sel_hi:[1,0,1]
	v_pk_fma_f32 v[138:139], v[138:139], v[100:101], v[194:195] op_sel_hi:[1,0,1]
	v_pk_fma_f32 v[140:141], v[140:141], v[100:101], v[196:197] op_sel_hi:[1,0,1]
	v_pk_fma_f32 v[126:127], v[126:127], v[102:103], v[198:199] op_sel_hi:[1,0,1]
	v_pk_fma_f32 v[128:129], v[128:129], v[102:103], v[200:201] op_sel_hi:[1,0,1]
	v_pk_fma_f32 v[122:123], v[122:123], v[104:105], v[202:203] op_sel_hi:[1,0,1]
	v_pk_fma_f32 v[124:125], v[124:125], v[104:105], v[204:205] op_sel_hi:[1,0,1]
	global_store_dword v164, v142, s[100:101]
	global_store_dword v164, v138, s[100:101] offset:64
	global_store_dword v164, v126, s[100:101] offset:512
	global_store_dword v164, v122, s[100:101] offset:576
	global_store_dword v165, v143, s[100:101]
	global_store_dword v165, v139, s[100:101] offset:64
	global_store_dword v165, v127, s[100:101] offset:512
	global_store_dword v165, v123, s[100:101] offset:576
	global_store_dword v166, v144, s[100:101]
	global_store_dword v166, v140, s[100:101] offset:64
	global_store_dword v166, v128, s[100:101] offset:512
	global_store_dword v166, v124, s[100:101] offset:576
	global_store_dword v167, v145, s[100:101]
	global_store_dword v167, v141, s[100:101] offset:64
	global_store_dword v167, v129, s[100:101] offset:512
	global_store_dword v167, v125, s[100:101] offset:576
	s_add_u32 s100, s100, 0x20000
	s_addc_u32 s101, s101, 0
	global_load_dword v190, v164, s[98:99]
	global_load_dword v194, v164, s[98:99] offset:64
	global_load_dword v198, v164, s[98:99] offset:512
	global_load_dword v202, v164, s[98:99] offset:576
	global_load_dword v191, v165, s[98:99]
	global_load_dword v195, v165, s[98:99] offset:64
	global_load_dword v199, v165, s[98:99] offset:512
	global_load_dword v203, v165, s[98:99] offset:576
	global_load_dword v192, v166, s[98:99]
	global_load_dword v196, v166, s[98:99] offset:64
	global_load_dword v200, v166, s[98:99] offset:512
	global_load_dword v204, v166, s[98:99] offset:576
	global_load_dword v193, v167, s[98:99]
	global_load_dword v197, v167, s[98:99] offset:64
	global_load_dword v201, v167, s[98:99] offset:512
	global_load_dword v205, v167, s[98:99] offset:576
	s_add_u32 s98, s98, 0x20000
	s_addc_u32 s99, s99, 0
	s_waitcnt vmcnt(32)
	v_pk_fma_f32 v[134:135], v[134:135], v[98:99], v[152:153] op_sel_hi:[1,0,1]
	v_pk_fma_f32 v[136:137], v[136:137], v[98:99], v[154:155] op_sel_hi:[1,0,1]
	v_pk_fma_f32 v[130:131], v[130:131], v[100:101], v[156:157] op_sel_hi:[1,0,1]
	v_pk_fma_f32 v[132:133], v[132:133], v[100:101], v[158:159] op_sel_hi:[1,0,1]
	v_pk_fma_f32 v[118:119], v[118:119], v[102:103], v[106:107] op_sel_hi:[1,0,1]
	v_pk_fma_f32 v[120:121], v[120:121], v[102:103], v[108:109] op_sel_hi:[1,0,1]
	v_pk_fma_f32 v[114:115], v[114:115], v[104:105], v[110:111] op_sel_hi:[1,0,1]
	v_pk_fma_f32 v[116:117], v[116:117], v[104:105], v[112:113] op_sel_hi:[1,0,1]
	global_store_dword v164, v134, s[100:101]
	global_store_dword v164, v130, s[100:101] offset:64
	global_store_dword v164, v118, s[100:101] offset:512
	global_store_dword v164, v114, s[100:101] offset:576
	global_store_dword v165, v135, s[100:101]
	global_store_dword v165, v131, s[100:101] offset:64
	global_store_dword v165, v119, s[100:101] offset:512
	global_store_dword v165, v115, s[100:101] offset:576
	global_store_dword v166, v136, s[100:101]
	global_store_dword v166, v132, s[100:101] offset:64
	global_store_dword v166, v120, s[100:101] offset:512
	global_store_dword v166, v116, s[100:101] offset:576
	global_store_dword v167, v137, s[100:101]
	global_store_dword v167, v133, s[100:101] offset:64
	global_store_dword v167, v121, s[100:101] offset:512
	global_store_dword v167, v117, s[100:101] offset:576
	s_add_u32 s100, s100, 0x20000
	s_addc_u32 s101, s101, 0
	global_load_dword v152, v164, s[98:99]
	global_load_dword v156, v164, s[98:99] offset:64
	global_load_dword v106, v164, s[98:99] offset:512
	global_load_dword v110, v164, s[98:99] offset:576
	global_load_dword v153, v165, s[98:99]
	global_load_dword v157, v165, s[98:99] offset:64
	global_load_dword v107, v165, s[98:99] offset:512
	global_load_dword v111, v165, s[98:99] offset:576
	global_load_dword v154, v166, s[98:99]
	global_load_dword v158, v166, s[98:99] offset:64
	global_load_dword v108, v166, s[98:99] offset:512
	global_load_dword v112, v166, s[98:99] offset:576
	global_load_dword v155, v167, s[98:99]
	global_load_dword v159, v167, s[98:99] offset:64
	global_load_dword v109, v167, s[98:99] offset:512
	global_load_dword v113, v167, s[98:99] offset:576
	s_add_u32 s98, s98, 0xa0000
	s_addc_u32 s99, s99, 0
	s_waitcnt vmcnt(32)
	v_pk_fma_f32 v[94:95], v[94:95], v[98:99], v[190:191] op_sel_hi:[1,0,1]
	v_pk_fma_f32 v[96:97], v[96:97], v[98:99], v[192:193] op_sel_hi:[1,0,1]
	v_pk_fma_f32 v[90:91], v[90:91], v[100:101], v[194:195] op_sel_hi:[1,0,1]
	v_pk_fma_f32 v[92:93], v[92:93], v[100:101], v[196:197] op_sel_hi:[1,0,1]
	v_pk_fma_f32 v[78:79], v[78:79], v[102:103], v[198:199] op_sel_hi:[1,0,1]
	v_pk_fma_f32 v[80:81], v[80:81], v[102:103], v[200:201] op_sel_hi:[1,0,1]
	v_pk_fma_f32 v[74:75], v[74:75], v[104:105], v[202:203] op_sel_hi:[1,0,1]
	v_pk_fma_f32 v[76:77], v[76:77], v[104:105], v[204:205] op_sel_hi:[1,0,1]
	global_store_dword v164, v94, s[100:101]
	global_store_dword v164, v90, s[100:101] offset:64
	global_store_dword v164, v78, s[100:101] offset:512
	global_store_dword v164, v74, s[100:101] offset:576
	global_store_dword v165, v95, s[100:101]
	global_store_dword v165, v91, s[100:101] offset:64
	global_store_dword v165, v79, s[100:101] offset:512
	global_store_dword v165, v75, s[100:101] offset:576
	global_store_dword v166, v96, s[100:101]
	global_store_dword v166, v92, s[100:101] offset:64
	global_store_dword v166, v80, s[100:101] offset:512
	global_store_dword v166, v76, s[100:101] offset:576
	global_store_dword v167, v97, s[100:101]
	global_store_dword v167, v93, s[100:101] offset:64
	global_store_dword v167, v81, s[100:101] offset:512
	global_store_dword v167, v77, s[100:101] offset:576
	s_add_u32 s100, s100, 0x20000
	s_addc_u32 s101, s101, 0
	global_load_dword v190, v164, s[98:99]
	global_load_dword v194, v164, s[98:99] offset:64
	global_load_dword v198, v164, s[98:99] offset:512
	global_load_dword v202, v164, s[98:99] offset:576
	global_load_dword v191, v165, s[98:99]
	global_load_dword v195, v165, s[98:99] offset:64
	global_load_dword v199, v165, s[98:99] offset:512
	global_load_dword v203, v165, s[98:99] offset:576
	global_load_dword v192, v166, s[98:99]
	global_load_dword v196, v166, s[98:99] offset:64
	global_load_dword v200, v166, s[98:99] offset:512
	global_load_dword v204, v166, s[98:99] offset:576
	global_load_dword v193, v167, s[98:99]
	global_load_dword v197, v167, s[98:99] offset:64
	global_load_dword v201, v167, s[98:99] offset:512
	global_load_dword v205, v167, s[98:99] offset:576
	s_add_u32 s98, s98, 0x20000
	s_addc_u32 s99, s99, 0
	s_waitcnt vmcnt(32)
	v_pk_fma_f32 v[86:87], v[86:87], v[98:99], v[152:153] op_sel_hi:[1,0,1]
	v_pk_fma_f32 v[88:89], v[88:89], v[98:99], v[154:155] op_sel_hi:[1,0,1]
	v_pk_fma_f32 v[82:83], v[82:83], v[100:101], v[156:157] op_sel_hi:[1,0,1]
	v_pk_fma_f32 v[84:85], v[84:85], v[100:101], v[158:159] op_sel_hi:[1,0,1]
	v_pk_fma_f32 v[70:71], v[70:71], v[102:103], v[106:107] op_sel_hi:[1,0,1]
	v_pk_fma_f32 v[72:73], v[72:73], v[102:103], v[108:109] op_sel_hi:[1,0,1]
	v_pk_fma_f32 v[66:67], v[66:67], v[104:105], v[110:111] op_sel_hi:[1,0,1]
	v_pk_fma_f32 v[68:69], v[68:69], v[104:105], v[112:113] op_sel_hi:[1,0,1]
	global_store_dword v164, v86, s[100:101]
	global_store_dword v164, v82, s[100:101] offset:64
	global_store_dword v164, v70, s[100:101] offset:512
	global_store_dword v164, v66, s[100:101] offset:576
	global_store_dword v165, v87, s[100:101]
	global_store_dword v165, v83, s[100:101] offset:64
	global_store_dword v165, v71, s[100:101] offset:512
	global_store_dword v165, v67, s[100:101] offset:576
	global_store_dword v166, v88, s[100:101]
	global_store_dword v166, v84, s[100:101] offset:64
	global_store_dword v166, v72, s[100:101] offset:512
	global_store_dword v166, v68, s[100:101] offset:576
	global_store_dword v167, v89, s[100:101]
	global_store_dword v167, v85, s[100:101] offset:64
	global_store_dword v167, v73, s[100:101] offset:512
	global_store_dword v167, v69, s[100:101] offset:576
	s_add_u32 s100, s100, 0xa0000
	s_addc_u32 s101, s101, 0
	global_load_dword v152, v164, s[98:99]
	global_load_dword v156, v164, s[98:99] offset:64
	global_load_dword v106, v164, s[98:99] offset:512
	global_load_dword v110, v164, s[98:99] offset:576
	global_load_dword v153, v165, s[98:99]
	global_load_dword v157, v165, s[98:99] offset:64
	global_load_dword v107, v165, s[98:99] offset:512
	global_load_dword v111, v165, s[98:99] offset:576
	global_load_dword v154, v166, s[98:99]
	global_load_dword v158, v166, s[98:99] offset:64
	global_load_dword v108, v166, s[98:99] offset:512
	global_load_dword v112, v166, s[98:99] offset:576
	global_load_dword v155, v167, s[98:99]
	global_load_dword v159, v167, s[98:99] offset:64
	global_load_dword v109, v167, s[98:99] offset:512
	global_load_dword v113, v167, s[98:99] offset:576
	s_add_u32 s98, s98, 0x20000
	s_addc_u32 s99, s99, 0
	s_waitcnt vmcnt(32)
	v_pk_fma_f32 v[62:63], v[62:63], v[98:99], v[190:191] op_sel_hi:[1,0,1]
	v_pk_fma_f32 v[64:65], v[64:65], v[98:99], v[192:193] op_sel_hi:[1,0,1]
	v_pk_fma_f32 v[58:59], v[58:59], v[100:101], v[194:195] op_sel_hi:[1,0,1]
	v_pk_fma_f32 v[60:61], v[60:61], v[100:101], v[196:197] op_sel_hi:[1,0,1]
	v_pk_fma_f32 v[46:47], v[46:47], v[102:103], v[198:199] op_sel_hi:[1,0,1]
	v_pk_fma_f32 v[48:49], v[48:49], v[102:103], v[200:201] op_sel_hi:[1,0,1]
	v_pk_fma_f32 v[42:43], v[42:43], v[104:105], v[202:203] op_sel_hi:[1,0,1]
	v_pk_fma_f32 v[44:45], v[44:45], v[104:105], v[204:205] op_sel_hi:[1,0,1]
	global_store_dword v164, v62, s[100:101]
	global_store_dword v164, v58, s[100:101] offset:64
	global_store_dword v164, v46, s[100:101] offset:512
	global_store_dword v164, v42, s[100:101] offset:576
	global_store_dword v165, v63, s[100:101]
	global_store_dword v165, v59, s[100:101] offset:64
	global_store_dword v165, v47, s[100:101] offset:512
	global_store_dword v165, v43, s[100:101] offset:576
	global_store_dword v166, v64, s[100:101]
	global_store_dword v166, v60, s[100:101] offset:64
	global_store_dword v166, v48, s[100:101] offset:512
	global_store_dword v166, v44, s[100:101] offset:576
	global_store_dword v167, v65, s[100:101]
	global_store_dword v167, v61, s[100:101] offset:64
	global_store_dword v167, v49, s[100:101] offset:512
	global_store_dword v167, v45, s[100:101] offset:576
	s_add_u32 s100, s100, 0x20000
	s_addc_u32 s101, s101, 0
	global_load_dword v190, v164, s[98:99]
	global_load_dword v194, v164, s[98:99] offset:64
	global_load_dword v198, v164, s[98:99] offset:512
	global_load_dword v202, v164, s[98:99] offset:576
	global_load_dword v191, v165, s[98:99]
	global_load_dword v195, v165, s[98:99] offset:64
	global_load_dword v199, v165, s[98:99] offset:512
	global_load_dword v203, v165, s[98:99] offset:576
	global_load_dword v192, v166, s[98:99]
	global_load_dword v196, v166, s[98:99] offset:64
	global_load_dword v200, v166, s[98:99] offset:512
	global_load_dword v204, v166, s[98:99] offset:576
	global_load_dword v193, v167, s[98:99]
	global_load_dword v197, v167, s[98:99] offset:64
	global_load_dword v201, v167, s[98:99] offset:512
	global_load_dword v205, v167, s[98:99] offset:576
	s_add_u32 s98, s98, 0x20000
	s_addc_u32 s99, s99, 0
	s_waitcnt vmcnt(32)
	v_pk_fma_f32 v[54:55], v[54:55], v[98:99], v[152:153] op_sel_hi:[1,0,1]
	v_pk_fma_f32 v[56:57], v[56:57], v[98:99], v[154:155] op_sel_hi:[1,0,1]
	v_pk_fma_f32 v[50:51], v[50:51], v[100:101], v[156:157] op_sel_hi:[1,0,1]
	v_pk_fma_f32 v[52:53], v[52:53], v[100:101], v[158:159] op_sel_hi:[1,0,1]
	v_pk_fma_f32 v[38:39], v[38:39], v[102:103], v[106:107] op_sel_hi:[1,0,1]
	v_pk_fma_f32 v[40:41], v[40:41], v[102:103], v[108:109] op_sel_hi:[1,0,1]
	v_pk_fma_f32 v[34:35], v[34:35], v[104:105], v[110:111] op_sel_hi:[1,0,1]
	v_pk_fma_f32 v[36:37], v[36:37], v[104:105], v[112:113] op_sel_hi:[1,0,1]
	global_store_dword v164, v54, s[100:101]
	global_store_dword v164, v50, s[100:101] offset:64
	global_store_dword v164, v38, s[100:101] offset:512
	global_store_dword v164, v34, s[100:101] offset:576
	global_store_dword v165, v55, s[100:101]
	global_store_dword v165, v51, s[100:101] offset:64
	global_store_dword v165, v39, s[100:101] offset:512
	global_store_dword v165, v35, s[100:101] offset:576
	global_store_dword v166, v56, s[100:101]
	global_store_dword v166, v52, s[100:101] offset:64
	global_store_dword v166, v40, s[100:101] offset:512
	global_store_dword v166, v36, s[100:101] offset:576
	global_store_dword v167, v57, s[100:101]
	global_store_dword v167, v53, s[100:101] offset:64
	global_store_dword v167, v41, s[100:101] offset:512
	global_store_dword v167, v37, s[100:101] offset:576
	s_add_u32 s100, s100, 0x20000
	s_addc_u32 s101, s101, 0
	global_load_dword v152, v164, s[98:99]
	global_load_dword v156, v164, s[98:99] offset:64
	global_load_dword v106, v164, s[98:99] offset:512
	global_load_dword v110, v164, s[98:99] offset:576
	global_load_dword v153, v165, s[98:99]
	global_load_dword v157, v165, s[98:99] offset:64
	global_load_dword v107, v165, s[98:99] offset:512
	global_load_dword v111, v165, s[98:99] offset:576
	global_load_dword v154, v166, s[98:99]
	global_load_dword v158, v166, s[98:99] offset:64
	global_load_dword v108, v166, s[98:99] offset:512
	global_load_dword v112, v166, s[98:99] offset:576
	global_load_dword v155, v167, s[98:99]
	global_load_dword v159, v167, s[98:99] offset:64
	global_load_dword v109, v167, s[98:99] offset:512
	global_load_dword v113, v167, s[98:99] offset:576
	s_waitcnt vmcnt(32)
	v_pk_fma_f32 v[28:29], v[28:29], v[98:99], v[190:191] op_sel_hi:[1,0,1]
	v_pk_fma_f32 v[30:31], v[30:31], v[98:99], v[192:193] op_sel_hi:[1,0,1]
	v_pk_fma_f32 v[24:25], v[24:25], v[100:101], v[194:195] op_sel_hi:[1,0,1]
	v_pk_fma_f32 v[26:27], v[26:27], v[100:101], v[196:197] op_sel_hi:[1,0,1]
	v_pk_fma_f32 v[12:13], v[12:13], v[102:103], v[198:199] op_sel_hi:[1,0,1]
	v_pk_fma_f32 v[14:15], v[14:15], v[102:103], v[200:201] op_sel_hi:[1,0,1]
	v_pk_fma_f32 v[8:9], v[8:9], v[104:105], v[202:203] op_sel_hi:[1,0,1]
	v_pk_fma_f32 v[10:11], v[10:11], v[104:105], v[204:205] op_sel_hi:[1,0,1]
	global_store_dword v164, v28, s[100:101]
	global_store_dword v164, v24, s[100:101] offset:64
	global_store_dword v164, v12, s[100:101] offset:512
	global_store_dword v164, v8, s[100:101] offset:576
	global_store_dword v165, v29, s[100:101]
	global_store_dword v165, v25, s[100:101] offset:64
	global_store_dword v165, v13, s[100:101] offset:512
	global_store_dword v165, v9, s[100:101] offset:576
	global_store_dword v166, v30, s[100:101]
	global_store_dword v166, v26, s[100:101] offset:64
	global_store_dword v166, v14, s[100:101] offset:512
	global_store_dword v166, v10, s[100:101] offset:576
	global_store_dword v167, v31, s[100:101]
	global_store_dword v167, v27, s[100:101] offset:64
	global_store_dword v167, v15, s[100:101] offset:512
	global_store_dword v167, v11, s[100:101] offset:576
	s_add_u32 s100, s100, 0x20000
	s_addc_u32 s101, s101, 0
	s_waitcnt vmcnt(16)
	v_pk_fma_f32 v[20:21], v[20:21], v[98:99], v[152:153] op_sel_hi:[1,0,1]
	v_pk_fma_f32 v[22:23], v[22:23], v[98:99], v[154:155] op_sel_hi:[1,0,1]
	v_pk_fma_f32 v[16:17], v[16:17], v[100:101], v[156:157] op_sel_hi:[1,0,1]
	v_pk_fma_f32 v[18:19], v[18:19], v[100:101], v[158:159] op_sel_hi:[1,0,1]
	v_pk_fma_f32 v[4:5], v[4:5], v[102:103], v[106:107] op_sel_hi:[1,0,1]
	v_pk_fma_f32 v[6:7], v[6:7], v[102:103], v[108:109] op_sel_hi:[1,0,1]
	v_pk_fma_f32 v[0:1], v[0:1], v[104:105], v[110:111] op_sel_hi:[1,0,1]
	v_pk_fma_f32 v[2:3], v[2:3], v[104:105], v[112:113] op_sel_hi:[1,0,1]
	global_store_dword v164, v20, s[100:101]
	global_store_dword v164, v16, s[100:101] offset:64
	global_store_dword v164, v4, s[100:101] offset:512
	global_store_dword v164, v0, s[100:101] offset:576
	global_store_dword v165, v21, s[100:101]
	global_store_dword v165, v17, s[100:101] offset:64
	global_store_dword v165, v5, s[100:101] offset:512
	global_store_dword v165, v1, s[100:101] offset:576
	global_store_dword v166, v22, s[100:101]
	global_store_dword v166, v18, s[100:101] offset:64
	global_store_dword v166, v6, s[100:101] offset:512
	global_store_dword v166, v2, s[100:101] offset:576
	global_store_dword v167, v23, s[100:101]
	global_store_dword v167, v19, s[100:101] offset:64
	global_store_dword v167, v7, s[100:101] offset:512
	global_store_dword v167, v3, s[100:101] offset:576
	s_mov_b64 s[14:15], -1
	s_andn2_b64 vcc, exec, s[2:3]
	s_cbranch_vccnz .LBB0_860
	s_andn2_b64 vcc, exec, s[0:1]
	s_cbranch_vccnz .LBB0_859
	s_barrier
	s_branch .LBB0_859
